# raise wave priority before the ping-pong handoff barriers so the first MFMA follows barrier release directly
# speedup vs baseline: 1.0016x; 1.0016x over previous
.LBB0_1283:
	v_exp_f32_e32 v64, v64
	v_exp_f32_e32 v65, v65
	v_exp_f32_e32 v66, v66
	v_exp_f32_e32 v67, v67
	v_exp_f32_e32 v68, v68
	v_add_f32_e32 v208, v64, v65
	v_exp_f32_e32 v69, v69
	v_exp_f32_e32 v70, v70
	v_add_f32_e32 v208, v66, v208
	v_exp_f32_e32 v71, v71
	v_add_f32_e32 v208, v67, v208
	v_exp_f32_e32 v72, v72
	v_add_f32_e32 v208, v68, v208
	v_exp_f32_e32 v73, v73
	v_add_f32_e32 v208, v69, v208
	v_exp_f32_e32 v74, v74
	v_add_f32_e32 v208, v70, v208
	v_exp_f32_e32 v75, v75
	v_add_f32_e32 v208, v71, v208
	v_exp_f32_e32 v76, v76
	v_add_f32_e32 v208, v72, v208
	v_exp_f32_e32 v77, v77
	v_add_f32_e32 v208, v73, v208
	v_exp_f32_e32 v78, v78
	v_add_f32_e32 v208, v74, v208
	v_exp_f32_e32 v79, v79
	v_add_f32_e32 v208, v75, v208
	v_add_f32_e32 v208, v76, v208
	v_add_f32_e32 v208, v77, v208
	v_add_f32_e32 v208, v78, v208
	v_add_f32_e32 v208, v79, v208
	v_add_f32_e32 v235, v235, v208
	v_cvt_pk_bf16_f32 v64, v64, v65
	v_cvt_pk_bf16_f32 v65, v66, v67
	v_cvt_pk_bf16_f32 v66, v68, v69
	v_cvt_pk_bf16_f32 v67, v70, v71
	v_cvt_pk_bf16_f32 v68, v72, v73
	v_cvt_pk_bf16_f32 v69, v74, v75
	v_cvt_pk_bf16_f32 v70, v76, v77
	v_cvt_pk_bf16_f32 v71, v78, v79
	s_waitcnt lgkmcnt(0)
	s_setprio 1
	s_barrier
	v_mfma_f32_32x32x16_bf16 v[48:63], v[180:183], v[64:67], v[48:63]
	v_mfma_f32_32x32x16_bf16 v[32:47], v[196:199], v[64:67], v[32:47]
	v_mfma_f32_32x32x16_bf16 v[16:31], v[188:191], v[64:67], v[16:31]
	v_mfma_f32_32x32x16_bf16 v[0:15], v[200:203], v[64:67], v[0:15]
	v_mfma_f32_32x32x16_bf16 v[48:63], v[176:179], v[68:71], v[48:63]
	v_mfma_f32_32x32x16_bf16 v[32:47], v[204:207], v[68:71], v[32:47]
	v_mfma_f32_32x32x16_bf16 v[16:31], v[192:195], v[68:71], v[16:31]
	v_mfma_f32_32x32x16_bf16 v[0:15], v[184:187], v[68:71], v[0:15]
	s_setprio 0
	s_setprio 1
	v_mfma_f32_32x32x16_bf16 v[64:79], v[168:171], v[80:83], v[238:253]
	ds_read_b128 v[180:183], v237 offset:53312
	v_mfma_f32_32x32x16_bf16 v[64:79], v[160:163], v[84:87], v[64:79]
	ds_read_b128 v[176:179], v237 offset:53344
	v_mfma_f32_32x32x16_bf16 v[64:79], v[164:167], v[88:91], v[64:79]
	ds_read_b128 v[184:187], v237 offset:57920
	v_mfma_f32_32x32x16_bf16 v[64:79], v[152:155], v[92:95], v[64:79]
	ds_read_b128 v[192:195], v237 offset:62528
	v_mfma_f32_32x32x16_bf16 v[64:79], v[156:159], v[96:99], v[64:79]
	ds_read_b128 v[196:199], v217 offset:13888
	v_mfma_f32_32x32x16_bf16 v[64:79], v[128:131], v[100:103], v[64:79]
	ds_read_b128 v[188:191], v217 offset:13920
	v_mfma_f32_32x32x16_bf16 v[64:79], v[132:135], v[104:107], v[64:79]
	ds_read_b128 v[200:203], v237 offset:57952
	v_mfma_f32_32x32x16_bf16 v[64:79], v[136:139], v[108:111], v[64:79]
	ds_read_b128 v[204:207], v237 offset:62560
	v_mfma_f32_32x32x16_bf16 v[64:79], v[140:143], v[112:115], v[64:79]
	v_mfma_f32_32x32x16_bf16 v[64:79], v[144:147], v[116:119], v[64:79]
	v_mfma_f32_32x32x16_bf16 v[64:79], v[148:151], v[120:123], v[64:79]
	v_mfma_f32_32x32x16_bf16 v[64:79], v[172:175], v[124:127], v[64:79]
	s_setprio 0
	s_waitcnt vmcnt(0) lgkmcnt(0)
	s_barrier
	s_add_i32 vcc_lo, s15, 63
	s_cmp_le_i32 vcc_lo, s86
	s_cbranch_scc1 .LBB0_1285
	v_add_u32_e32 v208, s15, v232
	v_add_u32_e32 v237, 32, v208
	v_cmp_lt_i32_e32 vcc, v237, v228
	s_nop 5
	v_cndmask_b32_e32 v65, v213, v65, vcc
	v_cmp_le_i32_e32 vcc, v237, v228
	v_add_u32_e32 v237, 34, v208
	s_nop 0
	v_cndmask_b32_e32 v64, v213, v64, vcc
	v_cmp_le_i32_e32 vcc, v237, v228
	v_add_u32_e32 v237, 35, v208
	s_nop 0
	v_cndmask_b32_e32 v66, v213, v66, vcc
	v_cmp_le_i32_e32 vcc, v237, v228
	v_add_u32_e32 v237, 40, v208
	s_nop 0
	v_cndmask_b32_e32 v67, v213, v67, vcc
	v_cmp_le_i32_e32 vcc, v237, v228
	v_add_u32_e32 v237, 41, v208
	s_nop 0
	v_cndmask_b32_e32 v68, v213, v68, vcc
	v_cmp_le_i32_e32 vcc, v237, v228
	v_add_u32_e32 v237, 42, v208
	s_nop 0
	v_cndmask_b32_e32 v69, v213, v69, vcc
	v_cmp_le_i32_e32 vcc, v237, v228
	v_add_u32_e32 v237, 43, v208
	s_nop 0
	v_cndmask_b32_e32 v70, v213, v70, vcc
	v_cmp_le_i32_e32 vcc, v237, v228
	v_add_u32_e32 v237, 48, v208
	s_nop 0
	v_cndmask_b32_e32 v71, v213, v71, vcc
	v_cmp_le_i32_e32 vcc, v237, v228
	v_add_u32_e32 v237, 49, v208
	s_nop 0
	v_cndmask_b32_e32 v72, v213, v72, vcc
	v_cmp_le_i32_e32 vcc, v237, v228
	v_add_u32_e32 v237, 50, v208
	s_nop 0
	v_cndmask_b32_e32 v73, v213, v73, vcc
	v_cmp_le_i32_e32 vcc, v237, v228
	v_add_u32_e32 v237, 51, v208
	s_nop 0
	v_cndmask_b32_e32 v74, v213, v74, vcc
	v_cmp_le_i32_e32 vcc, v237, v228
	v_add_u32_e32 v237, 56, v208
	s_nop 0
	v_cndmask_b32_e32 v75, v213, v75, vcc
	v_cmp_le_i32_e32 vcc, v237, v228
	v_add_u32_e32 v237, 57, v208
	s_nop 0
	v_cndmask_b32_e32 v76, v213, v76, vcc
	v_cmp_le_i32_e32 vcc, v237, v228
	v_add_u32_e32 v237, 58, v208
	v_add_u32_e32 v208, 59, v208
	v_cndmask_b32_e32 v77, v213, v77, vcc
	v_cmp_le_i32_e32 vcc, v237, v228
	s_nop 1
	v_cndmask_b32_e32 v78, v213, v78, vcc
	v_cmp_le_i32_e32 vcc, v208, v228
	s_nop 1
	v_cndmask_b32_e32 v79, v213, v79, vcc

.LBB0_1289:
	s_cmp_ge_i32 s35, s89
	s_waitcnt vmcnt(0) lgkmcnt(0)
	s_cselect_b64 vcc, -1, 0
	s_or_b64 s[68:69], vcc, s[68:69]
	s_andn2_b64 s[100:101], s[70:71], s[68:69]
	s_bitcmp1_b32 s34, 0
	s_cselect_b32 s99, 0x6800, 0
	s_cselect_b32 s98, 0x4800, 0
	v_add_u32_e32 v72, s99, v230
	v_add_u32_e32 v73, s99, v231
	v_add_u32_e32 v237, s98, v234
	v_add_u32_e32 v217, 0xd000, v237
	s_and_b64 vcc, exec, s[100:101]
	s_waitcnt vmcnt(0) lgkmcnt(0)
	s_setprio 1
	s_barrier
	s_cbranch_vccz .Lpp_slow
	v_mfma_f32_32x32x16_bf16 v[48:63], v[180:183], v[64:67], v[48:63]
	ds_read_b128 v[168:171], v72
	ds_read_b128 v[160:163], v72 offset:32
	v_mfma_f32_32x32x16_bf16 v[32:47], v[184:187], v[64:67], v[32:47]
	ds_read_b128 v[164:167], v72 offset:64
	ds_read_b128 v[152:155], v72 offset:96
	s_add_i32 s15, s15, 64
	s_mov_b32 s35, s34
	v_mfma_f32_32x32x16_bf16 v[16:31], v[192:195], v[64:67], v[16:31]
	ds_read_b128 v[156:159], v72 offset:128
	ds_read_b128 v[128:131], v72 offset:160
	s_add_i32 s34, s34, 1
	s_cmp_ge_u32 s34, s87
	v_mfma_f32_32x32x16_bf16 v[0:15], v[196:199], v[64:67], v[0:15]
	ds_read_b128 v[132:135], v72 offset:192
	ds_read_b128 v[136:139], v72 offset:224
	s_cselect_b64 s[68:69], -1, 0
	s_mov_b64 s[70:71], -1
	v_mfma_f32_32x32x16_bf16 v[48:63], v[176:179], v[68:71], v[48:63]
	ds_read_b128 v[140:143], v73 offset:17408
	ds_read_b128 v[144:147], v73 offset:17440
	s_mov_b32 vcc_lo, s99
	v_mfma_f32_32x32x16_bf16 v[32:47], v[200:203], v[68:71], v[32:47]
	ds_read_b128 v[148:151], v73 offset:17472
	ds_read_b128 v[208:211], v73 offset:17504
	v_mfma_f32_32x32x16_bf16 v[16:31], v[204:207], v[68:71], v[16:31]
	v_mfma_f32_32x32x16_bf16 v[0:15], v[188:191], v[68:71], v[0:15]
	s_branch .Lfh
